# PB attention (live copy): staging de-serialised with clamp+cndmask, sb0 Q loads and sink load hoisted above staging, on top of inner-loop rewrite
# baseline (speedup 1.0000x reference)
; #define LAS __attribute__((address_space(3)))
; __device__ __forceinline__ void attn_unit(LAS unsigned char* lds, const bf16* PROJ, bf16* DA, const float* sinkl, int unit, int tid, int wid, int lane) {
;     ...
;     for (int hp = 0; hp < 2; ++hp) {
;         v4u kreg[3], vreg[3];
; #pragma unroll
;         for (int i = 0; i < 3; ++i) {
;             const int idx = tid + 512 * (3 * hp + i), c = idx >> 3, ch = idx & 7, s = s0 + c;
;             if (s >= 0 && s < SEQ) { const bf16* p = PROJ + (rowb + s) * INW + 1024 + hk * 64 + ch * 8; kreg[i] = *(const v4u*)p; vreg[i] = *(const v4u*)(p + 128); }
;             else { kreg[i] = (v4u){0u, 0u, 0u, 0u}; vreg[i] = (v4u){0u, 0u, 0u, 0u}; }
;         }
; #pragma unroll
;         for (int i = 0; i < 3; ++i) {
;             const int idx = tid + 512 * (3 * hp + i), c = idx >> 3, ch = idx & 7;
;             *(LAS v4u*)(Ks + c * KS_PITCH + ch * 8) = kreg[i];
;             LAS bf16* vp = Vt + (ch * 8) * VT_PITCH + c;
;             vp[0 * VT_PITCH] = (bf16)(vreg[i].x & 0xffffu); vp[1 * VT_PITCH] = (bf16)(vreg[i].x >> 16);
;             vp[2 * VT_PITCH] = (bf16)(vreg[i].y & 0xffffu); vp[3 * VT_PITCH] = (bf16)(vreg[i].y >> 16);
;             vp[4 * VT_PITCH] = (bf16)(vreg[i].z & 0xffffu); vp[5 * VT_PITCH] = (bf16)(vreg[i].z >> 16);
;             vp[6 * VT_PITCH] = (bf16)(vreg[i].w & 0xffffu); vp[7 * VT_PITCH] = (bf16)(vreg[i].w >> 16);
;         }
;     ...
;     const float sink2 = sinkl[hq] * LOG2E;
;     const float NEG = -INFINITY;
;     const bool edge_n = (n == 0) || (n == 31);
; #pragma unroll 1
;     for (int sb = 0; sb < 2; ++sb) {
;         const int a0 = 64 * (wid & 1) + 32 * sb, a = a0 + r32;
;         const size_t qrow = rowb + (size_t)n * 128 + a;
;         bf16x8 qf[4];
; #pragma unroll
;         for (int ks = 0; ks < 4; ++ks) qf[ks] = *(const bf16x8*)(PROJ + qrow * INW + 512 + hq * 64 + ks * 16 + hi * 8);
.LBB0_355:
	s_and_b64 vcc, exec, s[36:37]
	s_cbranch_vccz .LBB0_423
	v_lshlrev_b32_e32 v2, 3, v173
	v_ashrrev_i32_e32 v42, 3, v173
	v_readlane_b32 s13, v239, 10
	v_and_b32_e32 v41, 56, v2
	v_lshlrev_b32_e32 v38, 1, v41
	v_mov_b32_e32 v39, v66
	s_waitcnt lgkmcnt(0)
	v_readlane_b32 s6, v239, 6
	v_readlane_b32 s7, v239, 7
	v_readlane_b32 s12, v239, 9
	s_lshl_b64 s[24:25], s[70:71], 2
	v_readlane_b32 s32, v239, 11
	s_add_u32 s24, s32, s24
	v_readlane_b32 s32, v239, 12
	s_addc_u32 s25, s32, s25
	v_readlane_b32 s88, v238, 7
	v_readlane_b32 s89, v238, 8
	v_bfe_u32 v189, v173, 5, 1
	v_lshlrev_b32_e32 v192, 4, v189
	v_mov_b32_e32 v193, v66
	v_lshl_add_u64 v[192:193], s[88:89], 0, v[192:193]
	v_and_b32_e32 v189, 31, v173
	v_or_b32_e32 v189, s80, v189
	v_or_b32_e32 v189, s12, v189
	v_or_b32_e32 v189, s6, v189
	v_mad_u64_u32 v[192:193], s[88:89], v189, s82, v[192:193]
	v_mad_i32_i24 v193, s7, v201, v193
	global_load_dwordx4 v[68:71], v[192:193], off offset:1024
	global_load_dwordx4 v[72:75], v[192:193], off offset:1056
	global_load_dwordx4 v[76:79], v[192:193], off offset:1088
	global_load_dwordx4 v[80:83], v[192:193], off offset:1120
	global_load_dword v191, v66, s[24:25]
	v_readlane_b32 s72, v238, 5
	v_readlane_b32 s73, v238, 6
	s_movk_i32 s84, 0x1000
	v_add_u32_e32 v2, 0x200, v173
	v_ashrrev_i32_e32 v43, 3, v2
	v_add_u32_e32 v2, 0x400, v173
	v_ashrrev_i32_e32 v44, 3, v2
	v_add_u32_e32 v2, 0x600, v173
	v_ashrrev_i32_e32 v186, 3, v2
	v_add_u32_e32 v2, 0x800, v173
	v_ashrrev_i32_e32 v187, 3, v2
	v_add_u32_e32 v2, 0xa00, v173
	v_ashrrev_i32_e32 v188, 3, v2
	v_add_u32_e32 v189, s13, v42
	v_cmp_gt_u32_e64 s[28:29], s84, v189
	v_and_b32_e32 v189, 0xfff, v189
	v_or_b32_e32 v190, s6, v189
	v_mov_b64_e32 v[192:193], s[72:73]
	v_mad_u64_u32 v[192:193], s[88:89], v190, s82, v[192:193]
	v_mad_i32_i24 v193, s7, v201, v193
	v_lshl_add_u64 v[192:193], v[192:193], 0, v[38:39]
	global_load_dwordx4 v[26:29], v[192:193], off offset:2048
	global_load_dwordx4 v[174:177], v[192:193], off offset:2304
	v_add_u32_e32 v189, s13, v43
	v_cmp_gt_u32_e64 s[30:31], s84, v189
	v_and_b32_e32 v189, 0xfff, v189
	v_or_b32_e32 v190, s6, v189
	v_mov_b64_e32 v[192:193], s[72:73]
	v_mad_u64_u32 v[192:193], s[88:89], v190, s82, v[192:193]
	v_mad_i32_i24 v193, s7, v201, v193
	v_lshl_add_u64 v[192:193], v[192:193], 0, v[38:39]
	global_load_dwordx4 v[30:33], v[192:193], off offset:2048
	global_load_dwordx4 v[178:181], v[192:193], off offset:2304
	v_add_u32_e32 v189, s13, v44
	v_cmp_gt_u32_e64 s[34:35], s84, v189
	v_and_b32_e32 v189, 0xfff, v189
	v_or_b32_e32 v190, s6, v189
	v_mov_b64_e32 v[192:193], s[72:73]
	v_mad_u64_u32 v[192:193], s[88:89], v190, s82, v[192:193]
	v_mad_i32_i24 v193, s7, v201, v193
	v_lshl_add_u64 v[192:193], v[192:193], 0, v[38:39]
	global_load_dwordx4 v[34:37], v[192:193], off offset:2048
	global_load_dwordx4 v[182:185], v[192:193], off offset:2304
	v_add_u32_e32 v189, s13, v186
	v_cmp_gt_u32_e64 s[62:63], s84, v189
	v_and_b32_e32 v189, 0xfff, v189
	v_or_b32_e32 v190, s6, v189
	v_mov_b64_e32 v[192:193], s[72:73]
	v_mad_u64_u32 v[192:193], s[88:89], v190, s82, v[192:193]
	v_mad_i32_i24 v193, s7, v201, v193
	v_lshl_add_u64 v[192:193], v[192:193], 0, v[38:39]
	global_load_dwordx4 v[6:9], v[192:193], off offset:2048
	global_load_dwordx4 v[2:5], v[192:193], off offset:2304
	v_add_u32_e32 v189, s13, v187
	v_cmp_gt_u32_e64 s[74:75], s84, v189
	v_and_b32_e32 v189, 0xfff, v189
	v_or_b32_e32 v190, s6, v189
	v_mov_b64_e32 v[192:193], s[72:73]
	v_mad_u64_u32 v[192:193], s[88:89], v190, s82, v[192:193]
	v_mad_i32_i24 v193, s7, v201, v193
	v_lshl_add_u64 v[192:193], v[192:193], 0, v[38:39]
	global_load_dwordx4 v[14:17], v[192:193], off offset:2048
	global_load_dwordx4 v[10:13], v[192:193], off offset:2304
	v_add_u32_e32 v189, s13, v188
	v_cmp_gt_u32_e64 s[76:77], s84, v189
	v_and_b32_e32 v189, 0xfff, v189
	v_or_b32_e32 v190, s6, v189
	v_mov_b64_e32 v[192:193], s[72:73]
	v_mad_u64_u32 v[192:193], s[88:89], v190, s82, v[192:193]
	v_mad_i32_i24 v193, s7, v201, v193
	v_lshl_add_u64 v[192:193], v[192:193], 0, v[38:39]
	global_load_dwordx4 v[22:25], v[192:193], off offset:2048
	global_load_dwordx4 v[18:21], v[192:193], off offset:2304
	v_lshl_add_u32 v40, v41, 1, 0
	s_movk_i32 s32, 0x306
	v_mad_u32_u24 v41, v41, s32, v40
	s_waitcnt vmcnt(11)
	v_cndmask_b32_e64 v26, 0, v26, s[28:29]
	v_cndmask_b32_e64 v27, 0, v27, s[28:29]
	v_cndmask_b32_e64 v28, 0, v28, s[28:29]
	v_cndmask_b32_e64 v29, 0, v29, s[28:29]
	v_mad_u32_u24 v121, v42, s3, v40
	ds_write_b128 v121, v[26:29]
	s_waitcnt vmcnt(10)
	v_cndmask_b32_e64 v174, 0, v174, s[28:29]
	v_cndmask_b32_e64 v175, 0, v175, s[28:29]
	v_cndmask_b32_e64 v176, 0, v176, s[28:29]
	v_cndmask_b32_e64 v177, 0, v177, s[28:29]
	v_lshl_add_u32 v122, v42, 1, v41
	ds_write_b16 v122, v174 offset:55296
	ds_write_b16_d16_hi v122, v174 offset:56072
	ds_write_b16 v122, v175 offset:56848
	ds_write_b16_d16_hi v122, v175 offset:57624
	ds_write_b16 v122, v176 offset:58400
	ds_write_b16_d16_hi v122, v176 offset:59176
	ds_write_b16 v122, v177 offset:59952
	ds_write_b16_d16_hi v122, v177 offset:60728
	s_waitcnt vmcnt(9)
	v_cndmask_b32_e64 v30, 0, v30, s[30:31]
	v_cndmask_b32_e64 v31, 0, v31, s[30:31]
	v_cndmask_b32_e64 v32, 0, v32, s[30:31]
	v_cndmask_b32_e64 v33, 0, v33, s[30:31]
	v_mad_u32_u24 v121, v43, s3, v40
	ds_write_b128 v121, v[30:33]
	s_waitcnt vmcnt(8)
; #define LAS __attribute__((address_space(3)))
; __device__ __forceinline__ void attn_unit(LAS unsigned char* lds, const bf16* PROJ, bf16* DA, const float* sinkl, int unit, int tid, int wid, int lane) {
;     ...
; #pragma unroll
;         for (int i = 0; i < 3; ++i) {
;             const int idx = tid + 512 * (3 * hp + i), c = idx >> 3, ch = idx & 7;
;             *(LAS v4u*)(Ks + c * KS_PITCH + ch * 8) = kreg[i];
;             LAS bf16* vp = Vt + (ch * 8) * VT_PITCH + c;
;             vp[0 * VT_PITCH] = (bf16)(vreg[i].x & 0xffffu); vp[1 * VT_PITCH] = (bf16)(vreg[i].x >> 16);
;             vp[2 * VT_PITCH] = (bf16)(vreg[i].y & 0xffffu); vp[3 * VT_PITCH] = (bf16)(vreg[i].y >> 16);
;             vp[4 * VT_PITCH] = (bf16)(vreg[i].z & 0xffffu); vp[5 * VT_PITCH] = (bf16)(vreg[i].z >> 16);
;             vp[6 * VT_PITCH] = (bf16)(vreg[i].w & 0xffffu); vp[7 * VT_PITCH] = (bf16)(vreg[i].w >> 16);
;         }
;     }
;     __syncthreads();
;     const int r32 = lane & 31, hi = lane >> 5;
;     const int hq = hk * 4 + (wid >> 1);
;     const float slope2 = __builtin_amdgcn_exp2f(-(float)(hq + 1)) * LOG2E;
;     const float sink2 = sinkl[hq] * LOG2E;
;     const float NEG = -INFINITY;
;     const bool edge_n = (n == 0) || (n == 31);
; #pragma unroll 1
;     for (int sb = 0; sb < 2; ++sb) {
;         const int a0 = 64 * (wid & 1) + 32 * sb, a = a0 + r32;
;         const size_t qrow = rowb + (size_t)n * 128 + a;
;         bf16x8 qf[4];
; #pragma unroll
;         for (int ks = 0; ks < 4; ++ks) qf[ks] = *(const bf16x8*)(PROJ + qrow * INW + 512 + hq * 64 + ks * 16 + hi * 8);
;         float mrun = sink2, l = 0.f;
;         f32x16 o0, o1;
; #pragma unroll
;         for (int r = 0; r < 16; ++r) { o0[r] = 0.f; o1[r] = 0.f; }
;         const float fb0 = (float)(r32 + 128 - 4 * hi);
	v_cndmask_b32_e64 v178, 0, v178, s[30:31]
	v_cndmask_b32_e64 v179, 0, v179, s[30:31]
	v_cndmask_b32_e64 v180, 0, v180, s[30:31]
	v_cndmask_b32_e64 v181, 0, v181, s[30:31]
	v_lshl_add_u32 v122, v43, 1, v41
	ds_write_b16 v122, v178 offset:55296
	ds_write_b16_d16_hi v122, v178 offset:56072
	ds_write_b16 v122, v179 offset:56848
	ds_write_b16_d16_hi v122, v179 offset:57624
	ds_write_b16 v122, v180 offset:58400
	ds_write_b16_d16_hi v122, v180 offset:59176
	ds_write_b16 v122, v181 offset:59952
	ds_write_b16_d16_hi v122, v181 offset:60728
	s_waitcnt vmcnt(7)
	v_cndmask_b32_e64 v34, 0, v34, s[34:35]
	v_cndmask_b32_e64 v35, 0, v35, s[34:35]
	v_cndmask_b32_e64 v36, 0, v36, s[34:35]
	v_cndmask_b32_e64 v37, 0, v37, s[34:35]
	v_mad_u32_u24 v121, v44, s3, v40
	ds_write_b128 v121, v[34:37]
	s_waitcnt vmcnt(6)
	v_cndmask_b32_e64 v182, 0, v182, s[34:35]
	v_cndmask_b32_e64 v183, 0, v183, s[34:35]
	v_cndmask_b32_e64 v184, 0, v184, s[34:35]
	v_cndmask_b32_e64 v185, 0, v185, s[34:35]
	v_lshl_add_u32 v122, v44, 1, v41
	ds_write_b16 v122, v182 offset:55296
	ds_write_b16_d16_hi v122, v182 offset:56072
	ds_write_b16 v122, v183 offset:56848
	ds_write_b16_d16_hi v122, v183 offset:57624
	ds_write_b16 v122, v184 offset:58400
	ds_write_b16_d16_hi v122, v184 offset:59176
	ds_write_b16 v122, v185 offset:59952
	ds_write_b16_d16_hi v122, v185 offset:60728
	s_waitcnt vmcnt(5)
	v_cndmask_b32_e64 v6, 0, v6, s[62:63]
	v_cndmask_b32_e64 v7, 0, v7, s[62:63]
	v_cndmask_b32_e64 v8, 0, v8, s[62:63]
	v_cndmask_b32_e64 v9, 0, v9, s[62:63]
	v_mad_u32_u24 v121, v186, s3, v40
	ds_write_b128 v121, v[6:9]
	s_waitcnt vmcnt(4)
	v_cndmask_b32_e64 v2, 0, v2, s[62:63]
	v_cndmask_b32_e64 v3, 0, v3, s[62:63]
	v_cndmask_b32_e64 v4, 0, v4, s[62:63]
	v_cndmask_b32_e64 v5, 0, v5, s[62:63]
	v_lshl_add_u32 v122, v186, 1, v41
	ds_write_b16 v122, v2 offset:55296
	ds_write_b16_d16_hi v122, v2 offset:56072
	ds_write_b16 v122, v3 offset:56848
	ds_write_b16_d16_hi v122, v3 offset:57624
	ds_write_b16 v122, v4 offset:58400
	ds_write_b16_d16_hi v122, v4 offset:59176
	ds_write_b16 v122, v5 offset:59952
	ds_write_b16_d16_hi v122, v5 offset:60728
	s_waitcnt vmcnt(3)
	v_cndmask_b32_e64 v14, 0, v14, s[74:75]
	v_cndmask_b32_e64 v15, 0, v15, s[74:75]
	v_cndmask_b32_e64 v16, 0, v16, s[74:75]
	v_cndmask_b32_e64 v17, 0, v17, s[74:75]
	v_mad_u32_u24 v121, v187, s3, v40
	ds_write_b128 v121, v[14:17]
	s_waitcnt vmcnt(2)
	v_cndmask_b32_e64 v10, 0, v10, s[74:75]
	v_cndmask_b32_e64 v11, 0, v11, s[74:75]
	v_cndmask_b32_e64 v12, 0, v12, s[74:75]
	v_cndmask_b32_e64 v13, 0, v13, s[74:75]
	v_lshl_add_u32 v122, v187, 1, v41
	ds_write_b16 v122, v10 offset:55296
	ds_write_b16_d16_hi v122, v10 offset:56072
	ds_write_b16 v122, v11 offset:56848
	ds_write_b16_d16_hi v122, v11 offset:57624
	ds_write_b16 v122, v12 offset:58400
	ds_write_b16_d16_hi v122, v12 offset:59176
	ds_write_b16 v122, v13 offset:59952
	ds_write_b16_d16_hi v122, v13 offset:60728
	s_waitcnt vmcnt(1)
	v_cndmask_b32_e64 v22, 0, v22, s[76:77]
	v_cndmask_b32_e64 v23, 0, v23, s[76:77]
	v_cndmask_b32_e64 v24, 0, v24, s[76:77]
	v_cndmask_b32_e64 v25, 0, v25, s[76:77]
	v_mad_u32_u24 v121, v188, s3, v40
	ds_write_b128 v121, v[22:25]
	s_waitcnt vmcnt(0)
	v_cndmask_b32_e64 v18, 0, v18, s[76:77]
	v_cndmask_b32_e64 v19, 0, v19, s[76:77]
	v_cndmask_b32_e64 v20, 0, v20, s[76:77]
	v_cndmask_b32_e64 v21, 0, v21, s[76:77]
	v_lshl_add_u32 v122, v188, 1, v41
	ds_write_b16 v122, v18 offset:55296
	ds_write_b16_d16_hi v122, v18 offset:56072
	ds_write_b16 v122, v19 offset:56848
	ds_write_b16_d16_hi v122, v19 offset:57624
	ds_write_b16 v122, v20 offset:58400
	ds_write_b16_d16_hi v122, v20 offset:59176
	ds_write_b16 v122, v21 offset:59952
	ds_write_b16_d16_hi v122, v21 offset:60728
	s_waitcnt lgkmcnt(0)
	s_barrier
	v_mul_f32_e32 v204, 0x00000000, v162
	v_mul_f32_e32 v205, 0x3f800000, v162
	v_mul_f32_e32 v206, 0x40000000, v162
	v_mul_f32_e32 v207, 0x40400000, v162
	v_mul_f32_e32 v208, 0x41000000, v162
	v_mul_f32_e32 v209, 0x41100000, v162
	v_mul_f32_e32 v210, 0x41200000, v162
	v_mul_f32_e32 v211, 0x41300000, v162
	v_mul_f32_e32 v212, 0x41800000, v162
	v_mul_f32_e32 v213, 0x41880000, v162
	v_mul_f32_e32 v214, 0x41900000, v162
	v_mul_f32_e32 v215, 0x41980000, v162
	v_mul_f32_e32 v216, 0x41c00000, v162
	v_mul_f32_e32 v217, 0x41c80000, v162
	v_mul_f32_e32 v218, 0x41d00000, v162
	v_mul_f32_e32 v219, 0x41d80000, v162
	v_and_b32_e32 v67, 63, v173
	v_bfe_u32 v2, v173, 5, 1
	v_readlane_b32 s24, v238, 7
	v_and_b32_e32 v85, 31, v173
	v_lshlrev_b32_e32 v4, 3, v2
	v_lshlrev_b32_e32 v5, 2, v2
	v_lshlrev_b32_e32 v2, 4, v2
	v_or_b32_e32 v6, 32, v67
	v_readlane_b32 s25, v238, 8
	v_mul_u32_u24_e32 v7, 0x308, v85
	v_mul_u32_u24_e32 v8, 0x308, v6
	v_readlane_b32 s13, v238, 15
	v_add_u32_e32 v84, 0, v2
	v_sub_u32_e32 v95, v85, v5
	v_add3_u32 v96, v8, v4, s13
	v_add3_u32 v97, v7, v4, s13
	v_readlane_b32 s13, v238, 19
	v_add_u32_e32 v99, s80, v6
	s_mov_b32 s36, 0
	v_sub_u32_e32 v98, s13, v5
	s_mov_b64 s[38:39], -1
	s_mov_b32 s23, 0
	v_mul_f32_e32 v94, 0x3fb8aa3b, v191
	v_mov_b32_e32 v3, v66
	v_lshl_add_u64 v[86:87], s[24:25], 0, v[2:3]
	v_readlane_b32 s24, v238, 9
	v_readlane_b32 s25, v238, 10
	s_nop 1
	v_lshl_add_u64 v[88:89], s[24:25], 0, v[2:3]
	s_branch .LBB0_380

; #define ATT_QK(dst, cblk) do { _Pragma("unroll") for (int r = 0; r < 16; ++r) dst[r] = 0.f; \
;             _Pragma("unroll") for (int ks = 0; ks < 4; ++ks) { const bf16x8 kf = *(const LAS bf16x8*)(Ks + ((cblk) + r32) * KS_PITCH + ks * 16 + hi * 8); \
;                 dst = __builtin_amdgcn_mfma_f32_32x32x16_bf16(kf, qf[ks], dst, 0, 0, 0); } } while (0)
; __device__ __forceinline__ void attn_unit(LAS unsigned char* lds, const bf16* PROJ, bf16* DA, const float* sinkl, int unit, int tid, int wid, int lane) {
;     ...
;         const int a0 = 64 * (wid & 1) + 32 * sb, a = a0 + r32;
;         const size_t qrow = rowb + (size_t)n * 128 + a;
;         bf16x8 qf[4];
; #pragma unroll
;         for (int ks = 0; ks < 4; ++ks) qf[ks] = *(const bf16x8*)(PROJ + qrow * INW + 512 + hq * 64 + ks * 16 + hi * 8);
;         float mrun = sink2, l = 0.f;
;         f32x16 o0, o1;
; #pragma unroll
;         for (int r = 0; r < 16; ++r) { o0[r] = 0.f; o1[r] = 0.f; }
;         const float fb0 = (float)(r32 + 128 - 4 * hi);
;         f32x16 pn;
;     ...
;         ATT_QK(pn, a0);
.LBB0_380:
	s_or_b32 s24, s23, s80
	v_or_b32_e32 v4, s24, v85
	v_or_b32_e32 v2, s12, v4
	v_or_b32_e32 v90, s6, v2
	v_mad_u64_u32 v[2:3], s[24:25], v90, s82, v[86:87]
	v_mad_i32_i24 v3, s7, v201, v3
	s_cmp_eq_u32 s23, 0
	s_cbranch_scc1 .Lq_skip1
	global_load_dwordx4 v[68:71], v[2:3], off offset:1024
	global_load_dwordx4 v[72:75], v[2:3], off offset:1056
	global_load_dwordx4 v[76:79], v[2:3], off offset:1088
	global_load_dwordx4 v[80:83], v[2:3], off offset:1120
.Lq_skip1:
	v_mad_u32_u24 v26, v4, s3, v84
	ds_read_b128 v[18:21], v26
	ds_read_b128 v[22:25], v26 offset:32
	s_mov_b32 s37, s36
	s_xor_b64 s[70:71], s[38:39], -1
	s_mov_b32 s38, s36
	s_mov_b32 s39, s36
	s_mov_b32 s40, s36
	s_mov_b32 s41, s36
	s_mov_b32 s42, s36
	s_mov_b32 s43, s36
	s_mov_b32 s44, s36
	s_mov_b32 s45, s36
	s_mov_b32 s46, s36
	s_mov_b32 s47, s36
	s_mov_b32 s48, s36
	s_mov_b32 s49, s36
	s_mov_b32 s50, s36
	s_mov_b32 s51, s36
	v_mov_b64_e32 v[2:3], s[36:37]
	v_mov_b64_e32 v[16:17], s[50:51]
	s_lshl_b32 s24, s23, 1
	v_mov_b64_e32 v[4:5], s[38:39]
	v_mov_b64_e32 v[6:7], s[40:41]
	v_mov_b64_e32 v[8:9], s[42:43]
	v_mov_b64_e32 v[10:11], s[44:45]
	v_mov_b64_e32 v[12:13], s[46:47]
	v_mov_b64_e32 v[14:15], s[48:49]
	v_add_u32_e32 v100, s24, v96
	v_add_u32_e32 v101, s24, v97
	v_mov_b32_e32 v91, s7
	v_subrev_u32_e32 v102, s23, v98
	v_mov_b32_e32 v103, v94
	s_waitcnt vmcnt(3) lgkmcnt(1)
	v_mfma_f32_32x32x16_bf16 v[50:65], v[18:21], v[68:71], 0
	ds_read_b128 v[18:21], v26 offset:64
	s_waitcnt vmcnt(2) lgkmcnt(1)
	v_mfma_f32_32x32x16_bf16 v[50:65], v[22:25], v[72:75], v[50:65]
	s_waitcnt vmcnt(1) lgkmcnt(0)
	v_mfma_f32_32x32x16_bf16 v[50:65], v[18:21], v[76:79], v[50:65]
	ds_read_b128 v[18:21], v26 offset:96
	s_waitcnt vmcnt(0) lgkmcnt(0)
	v_mfma_f32_32x32x16_bf16 v[50:65], v[18:21], v[80:83], v[50:65]
	v_add_u32_e32 v18, s23, v99
	v_mad_u64_u32 v[92:93], s[24:25], v18, s3, v[84:85]
	v_mov_b64_e32 v[32:33], v[16:17]
	v_mov_b32_e32 v93, 0
	s_mov_b32 s23, 0
	s_mov_b32 s24, 0
	s_nop 5
	v_mov_b64_e32 v[34:35], v[50:51]
	v_mov_b64_e32 v[30:31], v[14:15]
	v_mov_b64_e32 v[28:29], v[12:13]
	v_mov_b64_e32 v[26:27], v[10:11]
	v_mov_b64_e32 v[24:25], v[8:9]
	v_mov_b64_e32 v[22:23], v[6:7]
	v_mov_b64_e32 v[20:21], v[4:5]
	v_mov_b64_e32 v[18:19], v[2:3]
	v_mov_b64_e32 v[36:37], v[52:53]
	v_mov_b64_e32 v[38:39], v[54:55]
	v_mov_b64_e32 v[40:41], v[56:57]
	v_mov_b64_e32 v[42:43], v[58:59]
	v_mov_b64_e32 v[44:45], v[60:61]
	v_mov_b64_e32 v[46:47], v[62:63]
	v_mov_b64_e32 v[48:49], v[64:65]
